# speedup vs baseline: 1.0006x; 1.0006x over previous
.LBB0_463:
	s_cmpk_gt_i32 s16, 0xff
	s_mov_b64 s[4:5], -1
	s_cbranch_scc1 .LBB0_457
	s_ashr_i32 s4, s16, 31
	s_lshr_b32 s4, s4, 26
	s_add_i32 s4, s16, s4
	s_andn2_b32 s4, s4, 63
	s_sub_i32 s5, s16, s4
	s_ashr_i32 s16, s5, 3
	s_lshl_b32 s5, s5, 3
	s_and_b32 s5, s5, 56
	s_or_b32 s4, s4, s5
	v_mov_b32_e32 v1, v170
	s_barrier
	s_or_b32 s4, s4, s18
	s_lshl_b32 s4, s4, 8
	v_lshlrev_b32_e32 v145, 4, v1
	v_bfe_u32 v35, v1, 2, 4
	v_ashrrev_i32_e32 v14, 2, v1
	v_add_u32_e32 v37, 0x1000, v145
	v_add_u32_e32 v38, 0x2000, v145
	v_add_u32_e32 v40, 0x3000, v145
	v_or_b32_e32 v12, s4, v35
	v_and_b32_e32 v6, -16, v14
	v_ashrrev_i32_e32 v19, 6, v37
	v_ashrrev_i32_e32 v10, 6, v38
	v_ashrrev_i32_e32 v13, 6, v40
	v_and_b32_e32 v34, 32, v1
	v_add_u32_e32 v6, v12, v6
	v_and_b32_e32 v8, -16, v19
	v_and_b32_e32 v39, -16, v10
	v_and_b32_e32 v41, -16, v13
	v_bitop3_b32 v2, v145, v34, 48 bitop3:0x6c
	v_mov_b32_e32 v3, v0
	v_ashrrev_i32_e32 v7, 31, v6
	v_add_u32_e32 v8, v8, v12
	v_add_u32_e32 v10, v39, v12
	v_add_u32_e32 v12, v41, v12
	s_ashr_i32 s17, s16, 31
	v_lshl_add_u64 v[4:5], s[36:37], 0, v[2:3]
	v_lshlrev_b64 v[6:7], 9, v[6:7]
	v_ashrrev_i32_e32 v9, 31, v8
	v_ashrrev_i32_e32 v11, 31, v10
	v_ashrrev_i32_e32 v13, 31, v12
	v_readfirstlane_b32 s5, v145
	s_lshl_b64 s[18:19], s[16:17], 16
	v_lshrrev_b32_e32 v18, 2, v1
	v_lshl_add_u64 v[6:7], v[4:5], 0, v[6:7]
	v_lshlrev_b64 v[8:9], 9, v[8:9]
	v_lshlrev_b64 v[10:11], 9, v[10:11]
	v_lshlrev_b64 v[12:13], 9, v[12:13]
	s_waitcnt vmcnt(0)
	s_mov_b32 m0, s5
	v_readfirstlane_b32 s5, v37
	s_add_u32 s26, s20, s18
	v_lshl_add_u64 v[8:9], v[4:5], 0, v[8:9]
	v_lshl_add_u64 v[10:11], v[4:5], 0, v[10:11]
	v_lshl_add_u64 v[4:5], v[4:5], 0, v[12:13]
	v_bfi_b32 v12, 15, v18, v14
	s_mov_b32 m0, s5
	v_readfirstlane_b32 s5, v38
	s_addc_u32 s27, s21, s19
	v_ashrrev_i32_e32 v13, 31, v12
	v_bfi_b32 v18, -16, v19, v18
	v_add_u32_e32 v42, 0x4000, v145
	s_mov_b32 m0, s5
	v_readfirstlane_b32 s5, v40
	v_lshl_add_u64 v[2:3], s[26:27], 0, v[2:3]
	v_lshlrev_b64 v[14:15], 9, v[12:13]
	v_ashrrev_i32_e32 v19, 31, v18
	v_add_u32_e32 v43, 0x5000, v145
	s_mov_b32 m0, s5
	v_readfirstlane_b32 s5, v42
	v_lshl_add_u64 v[16:17], v[2:3], 0, v[14:15]
	v_lshlrev_b64 v[20:21], 9, v[18:19]
	v_add_u32_e32 v44, 0x6000, v145
	s_mov_b32 m0, s5
	v_readfirstlane_b32 s5, v43
	v_and_b32_e32 v142, 15, v1
	v_lshl_add_u64 v[2:3], v[2:3], 0, v[20:21]
	v_bfe_u32 v143, v1, 4, 2
	v_lshlrev_b32_e32 v19, 6, v1
	v_lshlrev_b32_e32 v22, 2, v1
	v_add_u32_e32 v45, 0x7000, v145
	s_mov_b32 m0, s5
	v_readfirstlane_b32 s5, v44
	v_lshlrev_b32_e32 v13, 4, v143
	v_and_b32_e32 v24, 0x3c0, v19
	v_lshlrev_b32_e32 v25, 6, v142
	v_and_b32_e32 v26, 32, v22
	v_lshl_add_u64 v[22:23], v[6:7], 0, 64
	v_add_u32_e32 v46, 0x8000, v145
	s_mov_b32 m0, s5
	v_readfirstlane_b32 s5, v45
	v_add_u32_e32 v47, 0x9000, v145
	v_bitop3_b32 v149, v13, v26, v24 bitop3:0x36
	v_bitop3_b32 v144, v13, v26, v25 bitop3:0x36
	v_lshl_add_u64 v[24:25], v[8:9], 0, 64
	s_mov_b32 m0, s5
	v_readfirstlane_b32 s5, v46
	v_add_u32_e32 v48, 0xa000, v145
	v_lshl_add_u64 v[26:27], v[10:11], 0, 64
	s_mov_b32 m0, s5
	v_readfirstlane_b32 s5, v47
	v_add_u32_e32 v49, 0xb000, v145
	v_lshl_add_u64 v[28:29], v[4:5], 0, 64
	s_mov_b32 m0, s5
	v_readfirstlane_b32 s5, v48
	v_lshl_add_u64 v[30:31], v[16:17], 0, 64
	s_mov_b32 m0, s5
	v_readfirstlane_b32 s5, v49
	v_lshl_add_u64 v[32:33], v[2:3], 0, 64
	s_mov_b32 m0, s5
	v_and_b32_e32 v36, 48, v145
	v_lshl_add_u64 v[2:3], s[18:19], 0, v[20:21]
	v_bitop3_b32 v2, v2, v36, v34 bitop3:0xf6
	v_lshl_add_u64 v[130:131], s[12:13], 0, v[2:3]
	v_lshl_add_u64 v[2:3], s[18:19], 0, v[14:15]
	v_bitop3_b32 v2, v2, v36, v34 bitop3:0xf6
	v_lshl_add_u64 v[132:133], s[12:13], 0, v[2:3]
	v_add_u32_e32 v2, s4, v41
	v_or_b32_e32 v2, v2, v35
	v_ashrrev_i32_e32 v3, 31, v2
	v_lshlrev_b64 v[2:3], 9, v[2:3]
	v_bitop3_b32 v2, v2, v36, v34 bitop3:0xf6
	v_lshl_add_u64 v[134:135], s[14:15], 0, v[2:3]
	v_add_u32_e32 v2, s4, v39
	v_or_b32_e32 v2, v2, v35
	v_ashrrev_i32_e32 v3, 31, v2
	v_lshlrev_b64 v[2:3], 9, v[2:3]
	v_bitop3_b32 v2, v2, v36, v34 bitop3:0xf6
	v_lshl_add_u64 v[136:137], s[14:15], 0, v[2:3]
	v_add_u32_e32 v2, s4, v18
	v_ashrrev_i32_e32 v3, 31, v2
	v_lshlrev_b64 v[2:3], 9, v[2:3]
	v_bitop3_b32 v2, v2, v36, v34 bitop3:0xf6
	v_lshl_add_u64 v[138:139], s[14:15], 0, v[2:3]
	v_add_u32_e32 v2, s4, v12
	v_ashrrev_i32_e32 v3, 31, v2
	v_lshlrev_b64 v[2:3], 9, v[2:3]
	v_bitop3_b32 v2, v2, v36, v34 bitop3:0xf6
	v_lshl_add_u64 v[140:141], s[14:15], 0, v[2:3]
	v_mov_b32_e32 v2, 0
	v_and_b32_e32 v147, 0xfffff000, v19
	s_mov_b32 s5, 0
	s_mov_b64 s[18:19], 0
	v_mov_b32_e32 v3, v2
	v_mov_b32_e32 v4, v2
	v_mov_b32_e32 v5, v2
	v_mov_b32_e32 v6, v2
	v_mov_b32_e32 v7, v2
	v_mov_b32_e32 v8, v2
	v_mov_b32_e32 v9, v2
	v_mov_b32_e32 v10, v2
	v_mov_b32_e32 v11, v2
	v_mov_b32_e32 v12, v2
	v_mov_b32_e32 v13, v2
	v_mov_b32_e32 v14, v2
	v_mov_b32_e32 v15, v2
	v_mov_b32_e32 v16, v2
	v_mov_b32_e32 v17, v2
	v_mov_b32_e32 v18, v2
	v_mov_b32_e32 v19, v2
	v_mov_b32_e32 v20, v2
	v_mov_b32_e32 v21, v2
	v_mov_b32_e32 v26, v2
	v_mov_b32_e32 v27, v2
	v_mov_b32_e32 v28, v2
	v_mov_b32_e32 v29, v2
	v_mov_b32_e32 v38, v2
	v_mov_b32_e32 v39, v2
	v_mov_b32_e32 v40, v2
	v_mov_b32_e32 v41, v2
	v_mov_b32_e32 v54, v2
	v_mov_b32_e32 v55, v2
	v_mov_b32_e32 v56, v2
	v_mov_b32_e32 v57, v2
	v_mov_b32_e32 v22, v2
	v_mov_b32_e32 v23, v2
	v_mov_b32_e32 v24, v2
	v_mov_b32_e32 v25, v2
	v_mov_b32_e32 v30, v2
	v_mov_b32_e32 v31, v2
	v_mov_b32_e32 v32, v2
	v_mov_b32_e32 v33, v2
	v_mov_b32_e32 v34, v2
	v_mov_b32_e32 v35, v2
	v_mov_b32_e32 v36, v2
	v_mov_b32_e32 v37, v2
	v_mov_b32_e32 v42, v2
	v_mov_b32_e32 v43, v2
	v_mov_b32_e32 v44, v2
	v_mov_b32_e32 v45, v2
	v_mov_b32_e32 v46, v2
	v_mov_b32_e32 v47, v2
	v_mov_b32_e32 v48, v2
	v_mov_b32_e32 v49, v2
	v_mov_b32_e32 v58, v2
	v_mov_b32_e32 v59, v2
	v_mov_b32_e32 v60, v2
	v_mov_b32_e32 v61, v2
	v_mov_b32_e32 v70, v2
	v_mov_b32_e32 v71, v2
	v_mov_b32_e32 v72, v2
	v_mov_b32_e32 v73, v2
	v_mov_b32_e32 v86, v2
	v_mov_b32_e32 v87, v2
	v_mov_b32_e32 v88, v2
	v_mov_b32_e32 v89, v2
	v_mov_b32_e32 v50, v2
	v_mov_b32_e32 v51, v2
	v_mov_b32_e32 v52, v2
	v_mov_b32_e32 v53, v2
	v_mov_b32_e32 v62, v2
	v_mov_b32_e32 v63, v2
	v_mov_b32_e32 v64, v2
	v_mov_b32_e32 v65, v2
	v_mov_b32_e32 v66, v2
	v_mov_b32_e32 v67, v2
	v_mov_b32_e32 v68, v2
	v_mov_b32_e32 v69, v2
	v_mov_b32_e32 v74, v2
	v_mov_b32_e32 v75, v2
	v_mov_b32_e32 v76, v2
	v_mov_b32_e32 v77, v2
	v_mov_b32_e32 v78, v2
	v_mov_b32_e32 v79, v2
	v_mov_b32_e32 v80, v2
	v_mov_b32_e32 v81, v2
	v_mov_b32_e32 v90, v2
	v_mov_b32_e32 v91, v2
	v_mov_b32_e32 v92, v2
	v_mov_b32_e32 v93, v2
	v_mov_b32_e32 v102, v2
	v_mov_b32_e32 v103, v2
	v_mov_b32_e32 v104, v2
	v_mov_b32_e32 v105, v2
	v_mov_b32_e32 v114, v2
	v_mov_b32_e32 v115, v2
	v_mov_b32_e32 v116, v2
	v_mov_b32_e32 v117, v2
	v_mov_b32_e32 v82, v2
	v_mov_b32_e32 v83, v2
	v_mov_b32_e32 v84, v2
	v_mov_b32_e32 v85, v2
	v_mov_b32_e32 v94, v2
	v_mov_b32_e32 v95, v2
	v_mov_b32_e32 v96, v2
	v_mov_b32_e32 v97, v2
	v_mov_b32_e32 v98, v2
	v_mov_b32_e32 v99, v2
	v_mov_b32_e32 v100, v2
	v_mov_b32_e32 v101, v2
	v_mov_b32_e32 v106, v2
	v_mov_b32_e32 v107, v2
	v_mov_b32_e32 v108, v2
	v_mov_b32_e32 v109, v2
	v_mov_b32_e32 v110, v2
	v_mov_b32_e32 v111, v2
	v_mov_b32_e32 v112, v2
	v_mov_b32_e32 v113, v2
	v_mov_b32_e32 v118, v2
	v_mov_b32_e32 v119, v2
	v_mov_b32_e32 v120, v2
	v_mov_b32_e32 v121, v2
	v_mov_b32_e32 v122, v2
	v_mov_b32_e32 v123, v2
	v_mov_b32_e32 v124, v2
	v_mov_b32_e32 v125, v2
	v_mov_b32_e32 v126, v2
	v_mov_b32_e32 v127, v2
	v_mov_b32_e32 v128, v2
	v_mov_b32_e32 v129, v2
	v_and_b32_e32 v154, 63, v170
	v_lshrrev_b32_e32 v155, 3, v154
	v_and_b32_e32 v156, 7, v154
	v_xor_b32_e32 v156, v156, v155
	v_lshrrev_b32_e32 v157, 6, v170
	v_lshl_add_u32 v158, v157, 6, v155
	v_add_u32_e32 v158, s4, v158
	v_mul_u32_u24_e32 v224, 0x200, v158
	v_lshl_add_u32 v224, v156, 4, v224
	v_lshl_add_u32 v158, v157, 5, v155
	v_mul_u32_u24_e32 v225, 0x200, v158
	v_lshl_add_u32 v225, v156, 4, v225
	v_and_b32_e32 v155, 15, v154
	v_lshrrev_b32_e32 v156, 4, v154
	v_and_b32_e32 v158, 7, v155
	v_xor_b32_e32 v156, v156, v158
	v_lshlrev_b32_e32 v156, 4, v156
	v_lshl_add_u32 v229, v155, 7, v156
	v_lshl_add_u32 v227, v157, 13, v229
	v_xor_b32_e32 v228, 64, v227
	v_add_u32_e32 v229, 0x8000, v229
	v_xor_b32_e32 v230, 64, v229
	s_mov_b32 s18, s36
	s_mov_b32 s19, s37
	s_sub_u32 s32, s26, s36
	v_add_u32_e32 v225, s32, v225
	s_mov_b32 s25, 0
	v_readfirstlane_b32 s32, v145
	s_lshl_b32 m0, s32, 3
	v_mov_b32_e32 v226, v224
	global_load_lds_dwordx4 v226, s[18:19]
	s_add_u32 m0, m0, 0x400
	v_add_u32_e32 v226, 0x1000, v224
	global_load_lds_dwordx4 v226, s[18:19]
	s_add_u32 m0, m0, 0x400
	v_add_u32_e32 v226, 0x2000, v224
	global_load_lds_dwordx4 v226, s[18:19]
	s_add_u32 m0, m0, 0x400
	v_add_u32_e32 v226, 0x3000, v224
	global_load_lds_dwordx4 v226, s[18:19]
	s_add_u32 m0, m0, 0x400
	v_add_u32_e32 v226, 0x4000, v224
	global_load_lds_dwordx4 v226, s[18:19]
	s_add_u32 m0, m0, 0x400
	v_add_u32_e32 v226, 0x5000, v224
	global_load_lds_dwordx4 v226, s[18:19]
	s_add_u32 m0, m0, 0x400
	v_add_u32_e32 v226, 0x6000, v224
	global_load_lds_dwordx4 v226, s[18:19]
	s_add_u32 m0, m0, 0x400
	v_add_u32_e32 v226, 0x7000, v224
	global_load_lds_dwordx4 v226, s[18:19]
	v_readfirstlane_b32 s32, v145
	s_lshl_b32 s32, s32, 2
	s_add_u32 m0, s32, 0x8000
	v_mov_b32_e32 v226, v225
	global_load_lds_dwordx4 v226, s[18:19]
	s_add_u32 m0, m0, 0x400
	v_add_u32_e32 v226, 0x1000, v225
	global_load_lds_dwordx4 v226, s[18:19]
	s_add_u32 m0, m0, 0x400
	v_add_u32_e32 v226, 0x2000, v225
	global_load_lds_dwordx4 v226, s[18:19]
	s_add_u32 m0, m0, 0x400
	v_add_u32_e32 v226, 0x3000, v225
	global_load_lds_dwordx4 v226, s[18:19]
.Lbk64_465:
	s_waitcnt vmcnt(0)
	s_barrier
	ds_read_b128 v[192:195], v227
	ds_read_b128 v[196:199], v228
	ds_read_b128 v[200:203], v227 offset:2048
	ds_read_b128 v[204:207], v228 offset:2048
	ds_read_b128 v[208:211], v227 offset:4096
	ds_read_b128 v[212:215], v228 offset:4096
	ds_read_b128 v[216:219], v227 offset:6144
	ds_read_b128 v[220:223], v228 offset:6144
	s_add_u32 s18, s18, 0x80
	s_addc_u32 s19, s19, 0
	s_waitcnt lgkmcnt(0)
	s_barrier
	ds_read_b128 v[154:157], v229 offset:0
	ds_read_b128 v[158:161], v230 offset:0
	ds_read_b128 v[162:165], v229 offset:2048
	ds_read_b128 v[166:169], v230 offset:2048
	s_waitcnt lgkmcnt(2)
	v_mfma_f32_16x16x32_bf16 v[126:129], v[192:195], v[154:157], v[126:129]
	v_mfma_f32_16x16x32_bf16 v[114:117], v[200:203], v[154:157], v[114:117]
	v_mfma_f32_16x16x32_bf16 v[86:89], v[208:211], v[154:157], v[86:89]
	v_mfma_f32_16x16x32_bf16 v[54:57], v[216:219], v[154:157], v[54:57]
	v_readfirstlane_b32 s32, v145
	s_lshl_b32 m0, s32, 3
	v_mov_b32_e32 v226, v224
	global_load_lds_dwordx4 v226, s[18:19]
	v_mfma_f32_16x16x32_bf16 v[126:129], v[196:199], v[158:161], v[126:129]
	v_mfma_f32_16x16x32_bf16 v[114:117], v[204:207], v[158:161], v[114:117]
	v_mfma_f32_16x16x32_bf16 v[86:89], v[212:215], v[158:161], v[86:89]
	v_mfma_f32_16x16x32_bf16 v[54:57], v[220:223], v[158:161], v[54:57]
	s_add_u32 m0, m0, 0x400
	v_add_u32_e32 v226, 0x1000, v224
	global_load_lds_dwordx4 v226, s[18:19]
	ds_read_b128 v[154:157], v229 offset:4096
	ds_read_b128 v[158:161], v230 offset:4096
	s_waitcnt lgkmcnt(2)
	v_mfma_f32_16x16x32_bf16 v[122:125], v[192:195], v[162:165], v[122:125]
	v_mfma_f32_16x16x32_bf16 v[102:105], v[200:203], v[162:165], v[102:105]
	v_mfma_f32_16x16x32_bf16 v[70:73], v[208:211], v[162:165], v[70:73]
	v_mfma_f32_16x16x32_bf16 v[38:41], v[216:219], v[162:165], v[38:41]
	s_add_u32 m0, m0, 0x400
	v_add_u32_e32 v226, 0x2000, v224
	global_load_lds_dwordx4 v226, s[18:19]
	v_mfma_f32_16x16x32_bf16 v[122:125], v[196:199], v[166:169], v[122:125]
	v_mfma_f32_16x16x32_bf16 v[102:105], v[204:207], v[166:169], v[102:105]
	v_mfma_f32_16x16x32_bf16 v[70:73], v[212:215], v[166:169], v[70:73]
	v_mfma_f32_16x16x32_bf16 v[38:41], v[220:223], v[166:169], v[38:41]
	s_add_u32 m0, m0, 0x400
	v_add_u32_e32 v226, 0x3000, v224
	global_load_lds_dwordx4 v226, s[18:19]
	ds_read_b128 v[162:165], v229 offset:6144
	ds_read_b128 v[166:169], v230 offset:6144
	s_waitcnt lgkmcnt(2)
	v_mfma_f32_16x16x32_bf16 v[118:121], v[192:195], v[154:157], v[118:121]
	v_mfma_f32_16x16x32_bf16 v[90:93], v[200:203], v[154:157], v[90:93]
	v_mfma_f32_16x16x32_bf16 v[58:61], v[208:211], v[154:157], v[58:61]
	v_mfma_f32_16x16x32_bf16 v[26:29], v[216:219], v[154:157], v[26:29]
	s_add_u32 m0, m0, 0x400
	v_add_u32_e32 v226, 0x4000, v224
	global_load_lds_dwordx4 v226, s[18:19]
	v_mfma_f32_16x16x32_bf16 v[118:121], v[196:199], v[158:161], v[118:121]
	v_mfma_f32_16x16x32_bf16 v[90:93], v[204:207], v[158:161], v[90:93]
	v_mfma_f32_16x16x32_bf16 v[58:61], v[212:215], v[158:161], v[58:61]
	v_mfma_f32_16x16x32_bf16 v[26:29], v[220:223], v[158:161], v[26:29]
	s_add_u32 m0, m0, 0x400
	v_add_u32_e32 v226, 0x5000, v224
	global_load_lds_dwordx4 v226, s[18:19]
	ds_read_b128 v[154:157], v229 offset:8192
	ds_read_b128 v[158:161], v230 offset:8192
	s_waitcnt lgkmcnt(2)
	v_mfma_f32_16x16x32_bf16 v[110:113], v[192:195], v[162:165], v[110:113]
	v_mfma_f32_16x16x32_bf16 v[78:81], v[200:203], v[162:165], v[78:81]
	v_mfma_f32_16x16x32_bf16 v[46:49], v[208:211], v[162:165], v[46:49]
	v_mfma_f32_16x16x32_bf16 v[18:21], v[216:219], v[162:165], v[18:21]
	s_add_u32 m0, m0, 0x400
	v_add_u32_e32 v226, 0x6000, v224
	global_load_lds_dwordx4 v226, s[18:19]
	v_mfma_f32_16x16x32_bf16 v[110:113], v[196:199], v[166:169], v[110:113]
	v_mfma_f32_16x16x32_bf16 v[78:81], v[204:207], v[166:169], v[78:81]
	v_mfma_f32_16x16x32_bf16 v[46:49], v[212:215], v[166:169], v[46:49]
	v_mfma_f32_16x16x32_bf16 v[18:21], v[220:223], v[166:169], v[18:21]
	s_add_u32 m0, m0, 0x400
	v_add_u32_e32 v226, 0x7000, v224
	global_load_lds_dwordx4 v226, s[18:19]
	ds_read_b128 v[162:165], v229 offset:10240
	ds_read_b128 v[166:169], v230 offset:10240
	s_waitcnt lgkmcnt(2)
	v_mfma_f32_16x16x32_bf16 v[106:109], v[192:195], v[154:157], v[106:109]
	v_mfma_f32_16x16x32_bf16 v[74:77], v[200:203], v[154:157], v[74:77]
	v_mfma_f32_16x16x32_bf16 v[42:45], v[208:211], v[154:157], v[42:45]
	v_mfma_f32_16x16x32_bf16 v[14:17], v[216:219], v[154:157], v[14:17]
	s_add_u32 m0, s25, 5
	s_and_b32 m0, m0, 1
	s_lshl_b32 m0, m0, 14
	s_add_u32 m0, m0, 0x8000
	v_readfirstlane_b32 s32, v145
	s_lshl_b32 s32, s32, 2
	s_add_u32 m0, m0, s32
	v_mov_b32_e32 v226, v225
	global_load_lds_dwordx4 v226, s[18:19]
	v_mfma_f32_16x16x32_bf16 v[106:109], v[196:199], v[158:161], v[106:109]
	v_mfma_f32_16x16x32_bf16 v[74:77], v[204:207], v[158:161], v[74:77]
	v_mfma_f32_16x16x32_bf16 v[42:45], v[212:215], v[158:161], v[42:45]
	v_mfma_f32_16x16x32_bf16 v[14:17], v[220:223], v[158:161], v[14:17]
	s_add_u32 m0, m0, 0x400
	v_add_u32_e32 v226, 0x1000, v225
	global_load_lds_dwordx4 v226, s[18:19]
	ds_read_b128 v[154:157], v229 offset:12288
	ds_read_b128 v[158:161], v230 offset:12288
	s_waitcnt lgkmcnt(2)
	v_mfma_f32_16x16x32_bf16 v[98:101], v[192:195], v[162:165], v[98:101]
	v_mfma_f32_16x16x32_bf16 v[66:69], v[200:203], v[162:165], v[66:69]
	v_mfma_f32_16x16x32_bf16 v[34:37], v[208:211], v[162:165], v[34:37]
	v_mfma_f32_16x16x32_bf16 v[10:13], v[216:219], v[162:165], v[10:13]
	s_add_u32 m0, m0, 0x400
	v_add_u32_e32 v226, 0x2000, v225
	global_load_lds_dwordx4 v226, s[18:19]
	v_mfma_f32_16x16x32_bf16 v[98:101], v[196:199], v[166:169], v[98:101]
	v_mfma_f32_16x16x32_bf16 v[66:69], v[204:207], v[166:169], v[66:69]
	v_mfma_f32_16x16x32_bf16 v[34:37], v[212:215], v[166:169], v[34:37]
	v_mfma_f32_16x16x32_bf16 v[10:13], v[220:223], v[166:169], v[10:13]
	s_add_u32 m0, m0, 0x400
	v_add_u32_e32 v226, 0x3000, v225
	global_load_lds_dwordx4 v226, s[18:19]
	ds_read_b128 v[162:165], v229 offset:14336
	ds_read_b128 v[166:169], v230 offset:14336
	s_waitcnt lgkmcnt(2)
	v_mfma_f32_16x16x32_bf16 v[94:97], v[192:195], v[154:157], v[94:97]
	v_mfma_f32_16x16x32_bf16 v[62:65], v[200:203], v[154:157], v[62:65]
	v_mfma_f32_16x16x32_bf16 v[30:33], v[208:211], v[154:157], v[30:33]
	v_mfma_f32_16x16x32_bf16 v[6:9], v[216:219], v[154:157], v[6:9]
	v_mfma_f32_16x16x32_bf16 v[94:97], v[196:199], v[158:161], v[94:97]
	v_mfma_f32_16x16x32_bf16 v[62:65], v[204:207], v[158:161], v[62:65]
	v_mfma_f32_16x16x32_bf16 v[30:33], v[212:215], v[158:161], v[30:33]
	v_mfma_f32_16x16x32_bf16 v[6:9], v[220:223], v[158:161], v[6:9]
	s_waitcnt lgkmcnt(0)
	v_mfma_f32_16x16x32_bf16 v[82:85], v[192:195], v[162:165], v[82:85]
	v_mfma_f32_16x16x32_bf16 v[50:53], v[200:203], v[162:165], v[50:53]
	v_mfma_f32_16x16x32_bf16 v[22:25], v[208:211], v[162:165], v[22:25]
	v_mfma_f32_16x16x32_bf16 v[2:5], v[216:219], v[162:165], v[2:5]
	v_mfma_f32_16x16x32_bf16 v[82:85], v[196:199], v[166:169], v[82:85]
	v_mfma_f32_16x16x32_bf16 v[50:53], v[204:207], v[166:169], v[50:53]
	v_mfma_f32_16x16x32_bf16 v[22:25], v[212:215], v[166:169], v[22:25]
	v_mfma_f32_16x16x32_bf16 v[2:5], v[220:223], v[166:169], v[2:5]
	v_xor_b32_e32 v229, 0x4000, v229
	v_xor_b32_e32 v230, 0x4000, v230
	s_add_i32 s25, s25, 1
	s_cmp_lg_u32 s25, 3
	s_cbranch_scc1 .Lbk64_465
	s_waitcnt vmcnt(0)
	s_barrier
	ds_read_b128 v[192:195], v227
	ds_read_b128 v[196:199], v228
	ds_read_b128 v[200:203], v227 offset:2048
	ds_read_b128 v[204:207], v228 offset:2048
	ds_read_b128 v[208:211], v227 offset:4096
	ds_read_b128 v[212:215], v228 offset:4096
	ds_read_b128 v[216:219], v227 offset:6144
	ds_read_b128 v[220:223], v228 offset:6144
	s_waitcnt lgkmcnt(0)
	s_barrier
	ds_read_b128 v[154:157], v229 offset:0
	ds_read_b128 v[158:161], v230 offset:0
	ds_read_b128 v[162:165], v229 offset:2048
	ds_read_b128 v[166:169], v230 offset:2048
	s_waitcnt lgkmcnt(2)
	v_mfma_f32_16x16x32_bf16 v[126:129], v[192:195], v[154:157], v[126:129]
	v_mfma_f32_16x16x32_bf16 v[114:117], v[200:203], v[154:157], v[114:117]
	v_mfma_f32_16x16x32_bf16 v[86:89], v[208:211], v[154:157], v[86:89]
	v_mfma_f32_16x16x32_bf16 v[54:57], v[216:219], v[154:157], v[54:57]
	v_mfma_f32_16x16x32_bf16 v[126:129], v[196:199], v[158:161], v[126:129]
	v_mfma_f32_16x16x32_bf16 v[114:117], v[204:207], v[158:161], v[114:117]
	v_mfma_f32_16x16x32_bf16 v[86:89], v[212:215], v[158:161], v[86:89]
	v_mfma_f32_16x16x32_bf16 v[54:57], v[220:223], v[158:161], v[54:57]
	ds_read_b128 v[154:157], v229 offset:4096
	ds_read_b128 v[158:161], v230 offset:4096
	s_waitcnt lgkmcnt(2)
	v_mfma_f32_16x16x32_bf16 v[122:125], v[192:195], v[162:165], v[122:125]
	v_mfma_f32_16x16x32_bf16 v[102:105], v[200:203], v[162:165], v[102:105]
	v_mfma_f32_16x16x32_bf16 v[70:73], v[208:211], v[162:165], v[70:73]
	v_mfma_f32_16x16x32_bf16 v[38:41], v[216:219], v[162:165], v[38:41]
	v_mfma_f32_16x16x32_bf16 v[122:125], v[196:199], v[166:169], v[122:125]
	v_mfma_f32_16x16x32_bf16 v[102:105], v[204:207], v[166:169], v[102:105]
	v_mfma_f32_16x16x32_bf16 v[70:73], v[212:215], v[166:169], v[70:73]
	v_mfma_f32_16x16x32_bf16 v[38:41], v[220:223], v[166:169], v[38:41]
	ds_read_b128 v[162:165], v229 offset:6144
	ds_read_b128 v[166:169], v230 offset:6144
	s_waitcnt lgkmcnt(2)
	v_mfma_f32_16x16x32_bf16 v[118:121], v[192:195], v[154:157], v[118:121]
	v_mfma_f32_16x16x32_bf16 v[90:93], v[200:203], v[154:157], v[90:93]
	v_mfma_f32_16x16x32_bf16 v[58:61], v[208:211], v[154:157], v[58:61]
	v_mfma_f32_16x16x32_bf16 v[26:29], v[216:219], v[154:157], v[26:29]
	v_mfma_f32_16x16x32_bf16 v[118:121], v[196:199], v[158:161], v[118:121]
	v_mfma_f32_16x16x32_bf16 v[90:93], v[204:207], v[158:161], v[90:93]
	v_mfma_f32_16x16x32_bf16 v[58:61], v[212:215], v[158:161], v[58:61]
	v_mfma_f32_16x16x32_bf16 v[26:29], v[220:223], v[158:161], v[26:29]
	ds_read_b128 v[154:157], v229 offset:8192
	ds_read_b128 v[158:161], v230 offset:8192
	s_waitcnt lgkmcnt(2)
	v_mfma_f32_16x16x32_bf16 v[110:113], v[192:195], v[162:165], v[110:113]
	v_mfma_f32_16x16x32_bf16 v[78:81], v[200:203], v[162:165], v[78:81]
	v_mfma_f32_16x16x32_bf16 v[46:49], v[208:211], v[162:165], v[46:49]
	v_mfma_f32_16x16x32_bf16 v[18:21], v[216:219], v[162:165], v[18:21]
	v_mfma_f32_16x16x32_bf16 v[110:113], v[196:199], v[166:169], v[110:113]
	v_mfma_f32_16x16x32_bf16 v[78:81], v[204:207], v[166:169], v[78:81]
	v_mfma_f32_16x16x32_bf16 v[46:49], v[212:215], v[166:169], v[46:49]
	v_mfma_f32_16x16x32_bf16 v[18:21], v[220:223], v[166:169], v[18:21]
	ds_read_b128 v[162:165], v229 offset:10240
	ds_read_b128 v[166:169], v230 offset:10240
	s_waitcnt lgkmcnt(2)
	v_mfma_f32_16x16x32_bf16 v[106:109], v[192:195], v[154:157], v[106:109]
	v_mfma_f32_16x16x32_bf16 v[74:77], v[200:203], v[154:157], v[74:77]
	v_mfma_f32_16x16x32_bf16 v[42:45], v[208:211], v[154:157], v[42:45]
	v_mfma_f32_16x16x32_bf16 v[14:17], v[216:219], v[154:157], v[14:17]
	v_mfma_f32_16x16x32_bf16 v[106:109], v[196:199], v[158:161], v[106:109]
	v_mfma_f32_16x16x32_bf16 v[74:77], v[204:207], v[158:161], v[74:77]
	v_mfma_f32_16x16x32_bf16 v[42:45], v[212:215], v[158:161], v[42:45]
	v_mfma_f32_16x16x32_bf16 v[14:17], v[220:223], v[158:161], v[14:17]
	ds_read_b128 v[154:157], v229 offset:12288
	ds_read_b128 v[158:161], v230 offset:12288
	s_waitcnt lgkmcnt(2)
	v_mfma_f32_16x16x32_bf16 v[98:101], v[192:195], v[162:165], v[98:101]
	v_mfma_f32_16x16x32_bf16 v[66:69], v[200:203], v[162:165], v[66:69]
	v_mfma_f32_16x16x32_bf16 v[34:37], v[208:211], v[162:165], v[34:37]
	v_mfma_f32_16x16x32_bf16 v[10:13], v[216:219], v[162:165], v[10:13]
	v_mfma_f32_16x16x32_bf16 v[98:101], v[196:199], v[166:169], v[98:101]
	v_mfma_f32_16x16x32_bf16 v[66:69], v[204:207], v[166:169], v[66:69]
	v_mfma_f32_16x16x32_bf16 v[34:37], v[212:215], v[166:169], v[34:37]
	v_mfma_f32_16x16x32_bf16 v[10:13], v[220:223], v[166:169], v[10:13]
	ds_read_b128 v[162:165], v229 offset:14336
	ds_read_b128 v[166:169], v230 offset:14336
	s_waitcnt lgkmcnt(2)
	v_mfma_f32_16x16x32_bf16 v[94:97], v[192:195], v[154:157], v[94:97]
	v_mfma_f32_16x16x32_bf16 v[62:65], v[200:203], v[154:157], v[62:65]
	v_mfma_f32_16x16x32_bf16 v[30:33], v[208:211], v[154:157], v[30:33]
	v_mfma_f32_16x16x32_bf16 v[6:9], v[216:219], v[154:157], v[6:9]
	v_mfma_f32_16x16x32_bf16 v[94:97], v[196:199], v[158:161], v[94:97]
	v_mfma_f32_16x16x32_bf16 v[62:65], v[204:207], v[158:161], v[62:65]
	v_mfma_f32_16x16x32_bf16 v[30:33], v[212:215], v[158:161], v[30:33]
	v_mfma_f32_16x16x32_bf16 v[6:9], v[220:223], v[158:161], v[6:9]
	s_waitcnt lgkmcnt(0)
	v_mfma_f32_16x16x32_bf16 v[82:85], v[192:195], v[162:165], v[82:85]
	v_mfma_f32_16x16x32_bf16 v[50:53], v[200:203], v[162:165], v[50:53]
	v_mfma_f32_16x16x32_bf16 v[22:25], v[208:211], v[162:165], v[22:25]
	v_mfma_f32_16x16x32_bf16 v[2:5], v[216:219], v[162:165], v[2:5]
	v_mfma_f32_16x16x32_bf16 v[82:85], v[196:199], v[166:169], v[82:85]
	v_mfma_f32_16x16x32_bf16 v[50:53], v[204:207], v[166:169], v[50:53]
	v_mfma_f32_16x16x32_bf16 v[22:25], v[212:215], v[166:169], v[22:25]
	v_mfma_f32_16x16x32_bf16 v[2:5], v[220:223], v[166:169], v[2:5]
	s_nop 7
	s_nop 7
	s_waitcnt vmcnt(6)
	v_add_u32_e32 v145, v149, v147
	s_waitcnt vmcnt(0)
	s_waitcnt lgkmcnt(0)
	s_lshl_b32 s18, s16, 7
	s_ashr_i32 s19, s18, 31
	s_lshl_b64 s[18:19], s[18:19], 1
	v_and_b32_e32 v1, 0xfffffc0, v1
	v_lshl_or_b32 v1, v143, 2, v1
	v_mul_lo_u32 v1, v1, s33
	v_lshl_or_b32 v1, v142, 2, v1
	s_lshl_b32 s16, s16, 1
	s_ashr_i32 s17, s16, 31
	s_lshl_b64 s[16:17], s[16:17], 2
	s_add_i32 s24, s24, 1
	v_mov_b64_e32 v[158:159], v[62:63]
	v_mov_b64_e32 v[160:161], v[64:65]
	v_mov_b64_e32 v[162:163], v[30:31]
	v_mov_b64_e32 v[164:165], v[32:33]
	v_mov_b64_e32 v[130:131], v[22:23]
	v_mov_b64_e32 v[132:133], v[24:25]
	s_waitcnt lgkmcnt(0)
	v_mov_b64_e32 v[224:225], v[38:39]
	v_mov_b64_e32 v[226:227], v[40:41]
	v_mov_b64_e32 v[38:39], v[34:35]
	v_mov_b64_e32 v[40:41], v[36:37]
	v_mov_b64_e32 v[34:35], v[2:3]
	v_mov_b64_e32 v[36:37], v[4:5]
	s_nop 2
	v_mov_b32_e32 v2, v170
	v_mov_b64_e32 v[208:209], v[114:115]
	v_mov_b64_e32 v[210:211], v[116:117]
	v_add_u32_e32 v2, s4, v2
	v_ashrrev_i32_e32 v3, 31, v2
	v_lshlrev_b64 v[2:3], 11, v[2:3]
	v_lshl_add_u64 v[2:3], s[8:9], 0, v[2:3]
	v_lshl_add_u64 v[2:3], v[2:3], 0, s[18:19]
	v_mov_b64_e32 v[212:213], v[54:55]
	v_mov_b64_e32 v[214:215], v[56:57]
	v_mov_b64_e32 v[216:217], v[122:123]
	v_mov_b64_e32 v[218:219], v[124:125]
	v_mov_b64_e32 v[220:221], v[102:103]
	v_mov_b64_e32 v[222:223], v[104:105]
	v_mov_b64_e32 v[228:229], v[118:119]
	v_mov_b64_e32 v[230:231], v[120:121]
	v_mov_b64_e32 v[232:233], v[58:59]
	v_mov_b64_e32 v[234:235], v[60:61]
	v_mov_b64_e32 v[236:237], v[26:27]
	v_mov_b64_e32 v[238:239], v[28:29]
	v_mov_b64_e32 v[240:241], v[110:111]
	v_mov_b64_e32 v[242:243], v[112:113]
	v_mov_b64_e32 v[244:245], v[78:79]
	v_mov_b64_e32 v[246:247], v[80:81]
	v_mov_b64_e32 v[248:249], v[46:47]
	v_mov_b64_e32 v[250:251], v[48:49]
	v_mov_b64_e32 v[62:63], v[106:107]
	v_mov_b64_e32 v[64:65], v[108:109]
	v_mov_b64_e32 v[46:47], v[74:75]
	v_mov_b64_e32 v[48:49], v[76:77]
	v_mov_b64_e32 v[74:75], v[98:99]
	v_mov_b64_e32 v[76:77], v[100:101]
	v_mov_b64_e32 v[54:55], v[66:67]
	v_mov_b64_e32 v[56:57], v[68:69]
	v_mov_b64_e32 v[58:59], v[158:159]
	v_mov_b64_e32 v[60:61], v[160:161]
	v_mov_b64_e32 v[66:67], v[50:51]
	v_mov_b64_e32 v[68:69], v[52:53]
	flat_load_dwordx4 v[138:141], v[2:3]
	flat_load_dwordx4 v[122:125], v[2:3] offset:16
	flat_load_dwordx4 v[118:121], v[2:3] offset:32
	flat_load_dwordx4 v[114:117], v[2:3] offset:48
	flat_load_dwordx4 v[110:113], v[2:3] offset:64
	flat_load_dwordx4 v[106:109], v[2:3] offset:80
	flat_load_dwordx4 v[102:105], v[2:3] offset:96
	flat_load_dwordx4 v[98:101], v[2:3] offset:112
	s_waitcnt vmcnt(0) lgkmcnt(0)
	s_barrier
	s_nop 7
	ds_write2_b32 v1, v126, v216 offset1:16
	ds_write2_b32 v1, v127, v217 offset0:68 offset1:84
	ds_write2_b32 v1, v128, v218 offset0:136 offset1:152
	ds_write2_b32 v1, v129, v219 offset0:204 offset1:220
	ds_write2_b32 v1, v228, v240 offset0:32 offset1:48
	ds_write2_b32 v1, v229, v241 offset0:100 offset1:116
	ds_write2_b32 v1, v230, v242 offset0:168 offset1:184
	ds_write2_b32 v1, v231, v243 offset0:236 offset1:252
	v_mov_b64_e32 v[180:181], v[18:19]
	v_mov_b64_e32 v[182:183], v[20:21]
	v_mov_b64_e32 v[78:79], v[94:95]
	v_mov_b64_e32 v[80:81], v[96:97]
	v_add_u32_e32 v135, 0x3000, v1
	v_add_u32_e32 v134, 0x3400, v1
	v_mov_b32_e32 v136, v170
	v_mov_b64_e32 v[50:51], v[130:131]
	v_mov_b64_e32 v[52:53], v[132:133]
	v_lshlrev_b32_e32 v137, 16, v138
	s_nop 1
	v_add_u32_e32 v130, 0x1000, v1
	v_add_u32_e32 v131, 0x1400, v1
	v_add_u32_e32 v132, 0x2000, v1
	v_add_u32_e32 v133, 0x2400, v1
	ds_write2_b32 v130, v208, v220 offset0:64 offset1:80
	ds_write2_b32 v130, v209, v221 offset0:132 offset1:148
	ds_write2_b32 v130, v210, v222 offset0:200 offset1:216
	ds_write2_b32 v131, v211, v223 offset0:12 offset1:28
	ds_write2_b32 v130, v90, v244 offset0:96 offset1:112
	ds_write2_b32 v130, v91, v245 offset0:164 offset1:180
	ds_write2_b32 v130, v92, v246 offset0:232 offset1:248
	ds_write2_b32 v131, v93, v247 offset0:44 offset1:60
	ds_write2_b32 v132, v86, v70 offset0:128 offset1:144
	ds_write2_b32 v132, v87, v71 offset0:196 offset1:212
	ds_write2_b32 v133, v88, v72 offset0:8 offset1:24
	ds_write2_b32 v133, v89, v73 offset0:76 offset1:92
	ds_write2_b32 v132, v232, v248 offset0:160 offset1:176
	ds_write2_b32 v132, v233, v249 offset0:228 offset1:244
	ds_write2_b32 v133, v234, v250 offset0:40 offset1:56
	ds_write2_b32 v133, v235, v251 offset0:108 offset1:124
	ds_write2_b32 v135, v212, v224 offset0:192 offset1:208
	ds_write2_b32 v134, v213, v225 offset0:4 offset1:20
	ds_write2_b32 v134, v214, v226 offset0:72 offset1:88
	ds_write2_b32 v134, v215, v227 offset0:140 offset1:156
	ds_write2_b32 v135, v236, v180 offset0:224 offset1:240
	ds_write2_b32 v134, v237, v181 offset0:36 offset1:52
	ds_write2_b32 v134, v238, v182 offset0:104 offset1:120
	ds_write2_b32 v134, v239, v183 offset0:172 offset1:188
	s_waitcnt lgkmcnt(0)
	s_barrier
	v_mov_b64_e32 v[30:31], v[42:43]
	v_mov_b64_e32 v[32:33], v[44:45]
	v_add_u32_e32 v126, s4, v136
	v_ashrrev_i32_e32 v127, 31, v126
	v_lshlrev_b64 v[2:3], 11, v[126:127]
	v_lshl_add_u64 v[2:3], s[8:9], 0, v[2:3]
	v_lshl_add_u64 v[128:129], v[2:3], 0, s[18:19]
	v_mul_lo_u32 v136, v136, s33
	v_mov_b64_e32 v[18:19], v[14:15]
	v_mov_b64_e32 v[20:21], v[16:17]
	v_and_b32_e32 v138, 0xffff0000, v138
	v_mov_b64_e32 v[22:23], v[10:11]
	v_mov_b64_e32 v[24:25], v[12:13]
	v_mov_b64_e32 v[42:43], v[162:163]
	v_mov_b64_e32 v[44:45], v[164:165]
	v_mov_b64_e32 v[26:27], v[6:7]
	v_mov_b64_e32 v[28:29], v[8:9]
	flat_load_dwordx4 v[94:97], v[128:129] offset:128
	flat_load_dwordx4 v[90:93], v[128:129] offset:144
	flat_load_dwordx4 v[86:89], v[128:129] offset:160
	flat_load_dwordx4 v[70:73], v[128:129] offset:176
	flat_load_dwordx4 v[14:17], v[128:129] offset:192
	flat_load_dwordx4 v[10:13], v[128:129] offset:208
	flat_load_dwordx4 v[6:9], v[128:129] offset:224
	flat_load_dwordx4 v[2:5], v[128:129] offset:240
	ds_read_b128 v[142:145], v136
	ds_read_b128 v[154:157], v136 offset:16
	s_waitcnt lgkmcnt(0)
	v_add_f32_e32 v137, v142, v137
	v_add_f32_e32 v138, v143, v138
	v_cvt_pk_bf16_f32 v138, v137, v138
	v_lshlrev_b32_e32 v137, 16, v139
	v_and_b32_e32 v139, 0xffff0000, v139
	v_add_f32_e32 v137, v144, v137
	v_add_f32_e32 v139, v145, v139
	v_cvt_pk_bf16_f32 v139, v137, v139
	v_lshlrev_b32_e32 v137, 16, v140
	v_and_b32_e32 v140, 0xffff0000, v140
	v_add_f32_e32 v137, v154, v137
	v_add_f32_e32 v140, v155, v140
	v_cvt_pk_bf16_f32 v140, v137, v140
	v_lshlrev_b32_e32 v137, 16, v141
	v_and_b32_e32 v141, 0xffff0000, v141
	v_add_f32_e32 v137, v156, v137
	v_add_f32_e32 v141, v157, v141
	v_and_b32_e32 v142, 0xffff0000, v138
	v_cvt_pk_bf16_f32 v141, v137, v141
	v_lshlrev_b32_e32 v137, 16, v138
	v_mul_f32_e32 v153, v142, v142
	v_lshlrev_b32_e32 v143, 16, v139
	v_fmac_f32_e32 v153, v137, v137
	v_and_b32_e32 v144, 0xffff0000, v139
	v_fmac_f32_e32 v153, v143, v143
	v_lshlrev_b32_e32 v145, 16, v140
	v_fmac_f32_e32 v153, v144, v144
	flat_store_dwordx4 v[128:129], v[138:141]
	v_and_b32_e32 v147, 0xffff0000, v140
	v_lshlrev_b32_e32 v149, 16, v141
	v_and_b32_e32 v151, 0xffff0000, v141
	v_fmac_f32_e32 v153, v145, v145
	ds_read_b128 v[138:141], v136 offset:32
	ds_read_b128 v[142:145], v136 offset:48
	v_lshlrev_b32_e32 v137, 16, v122
	v_and_b32_e32 v122, 0xffff0000, v122
	v_fmac_f32_e32 v153, v147, v147
	s_waitcnt lgkmcnt(0)
	v_add_f32_e32 v137, v138, v137
	v_add_f32_e32 v122, v139, v122
	v_cvt_pk_bf16_f32 v122, v137, v122
	v_lshlrev_b32_e32 v137, 16, v123
	v_and_b32_e32 v123, 0xffff0000, v123
	v_add_f32_e32 v137, v140, v137
	v_add_f32_e32 v123, v141, v123
	v_cvt_pk_bf16_f32 v123, v137, v123
	v_lshlrev_b32_e32 v137, 16, v124
	v_and_b32_e32 v124, 0xffff0000, v124
	v_add_f32_e32 v137, v142, v137
	v_add_f32_e32 v124, v143, v124
	v_cvt_pk_bf16_f32 v124, v137, v124
	v_lshlrev_b32_e32 v137, 16, v125
	v_and_b32_e32 v125, 0xffff0000, v125
	v_add_f32_e32 v137, v144, v137
	v_add_f32_e32 v125, v145, v125
	v_and_b32_e32 v138, 0xffff0000, v122
	v_cvt_pk_bf16_f32 v125, v137, v125
	v_lshlrev_b32_e32 v137, 16, v122
	v_mul_f32_e32 v138, v138, v138
	v_lshlrev_b32_e32 v139, 16, v123
	v_fmac_f32_e32 v138, v137, v137
	v_and_b32_e32 v140, 0xffff0000, v123
	v_fmac_f32_e32 v138, v139, v139
	v_lshlrev_b32_e32 v141, 16, v124
	v_fmac_f32_e32 v138, v140, v140
	v_and_b32_e32 v142, 0xffff0000, v124
	v_fmac_f32_e32 v138, v141, v141
	v_lshlrev_b32_e32 v143, 16, v125
	v_fmac_f32_e32 v138, v142, v142
	v_fmac_f32_e32 v153, v149, v149
	v_and_b32_e32 v144, 0xffff0000, v125
	v_fmac_f32_e32 v138, v143, v143
	v_fmac_f32_e32 v153, v151, v151
	v_fmac_f32_e32 v138, v144, v144
	flat_store_dwordx4 v[128:129], v[122:125] offset:16
	v_add_f32_e32 v137, v153, v138
	ds_read_b128 v[122:125], v136 offset:64
	ds_read_b128 v[138:141], v136 offset:80
	v_lshlrev_b32_e32 v142, 16, v118
	v_and_b32_e32 v118, 0xffff0000, v118
	s_waitcnt lgkmcnt(0)
	v_add_f32_e32 v122, v122, v142
	v_add_f32_e32 v118, v123, v118
	v_cvt_pk_bf16_f32 v118, v122, v118
	v_lshlrev_b32_e32 v122, 16, v119
	v_and_b32_e32 v119, 0xffff0000, v119
	v_add_f32_e32 v122, v124, v122
	v_add_f32_e32 v119, v125, v119
	v_cvt_pk_bf16_f32 v119, v122, v119
	v_lshlrev_b32_e32 v122, 16, v120
	v_and_b32_e32 v120, 0xffff0000, v120
	v_add_f32_e32 v122, v138, v122
	v_add_f32_e32 v120, v139, v120
	v_cvt_pk_bf16_f32 v120, v122, v120
	v_lshlrev_b32_e32 v122, 16, v121
	v_and_b32_e32 v121, 0xffff0000, v121
	v_add_f32_e32 v122, v140, v122
	v_add_f32_e32 v121, v141, v121
	v_and_b32_e32 v123, 0xffff0000, v118
	v_cvt_pk_bf16_f32 v121, v122, v121
	v_lshlrev_b32_e32 v122, 16, v118
	v_mul_f32_e32 v123, v123, v123
	v_lshlrev_b32_e32 v124, 16, v119
	v_fmac_f32_e32 v123, v122, v122
	v_and_b32_e32 v125, 0xffff0000, v119
	v_fmac_f32_e32 v123, v124, v124
	v_lshlrev_b32_e32 v138, 16, v120
	v_fmac_f32_e32 v123, v125, v125
	v_and_b32_e32 v139, 0xffff0000, v120
	v_fmac_f32_e32 v123, v138, v138
	v_lshlrev_b32_e32 v140, 16, v121
	v_fmac_f32_e32 v123, v139, v139
	v_and_b32_e32 v141, 0xffff0000, v121
	v_fmac_f32_e32 v123, v140, v140
	v_fmac_f32_e32 v123, v141, v141
	flat_store_dwordx4 v[128:129], v[118:121] offset:32
	v_add_f32_e32 v137, v137, v123
	ds_read_b128 v[118:121], v136 offset:96
	ds_read_b128 v[122:125], v136 offset:112
	v_lshlrev_b32_e32 v138, 16, v114
	v_and_b32_e32 v114, 0xffff0000, v114
	s_waitcnt lgkmcnt(0)
	v_add_f32_e32 v118, v118, v138
	v_add_f32_e32 v114, v119, v114
	v_cvt_pk_bf16_f32 v114, v118, v114
	v_lshlrev_b32_e32 v118, 16, v115
	v_and_b32_e32 v115, 0xffff0000, v115
	v_add_f32_e32 v118, v120, v118
	v_add_f32_e32 v115, v121, v115
	v_cvt_pk_bf16_f32 v115, v118, v115
	v_lshlrev_b32_e32 v118, 16, v116
	v_and_b32_e32 v116, 0xffff0000, v116
	v_add_f32_e32 v118, v122, v118
	v_add_f32_e32 v116, v123, v116
	v_cvt_pk_bf16_f32 v116, v118, v116
	v_lshlrev_b32_e32 v118, 16, v117
	v_and_b32_e32 v117, 0xffff0000, v117
	v_add_f32_e32 v118, v124, v118
	v_add_f32_e32 v117, v125, v117
	v_and_b32_e32 v119, 0xffff0000, v114
	v_cvt_pk_bf16_f32 v117, v118, v117
	v_lshlrev_b32_e32 v118, 16, v114
	v_mul_f32_e32 v119, v119, v119
	v_lshlrev_b32_e32 v120, 16, v115
	v_fmac_f32_e32 v119, v118, v118
	v_and_b32_e32 v121, 0xffff0000, v115
	v_fmac_f32_e32 v119, v120, v120
	v_lshlrev_b32_e32 v122, 16, v116
	v_fmac_f32_e32 v119, v121, v121
	v_and_b32_e32 v123, 0xffff0000, v116
	v_fmac_f32_e32 v119, v122, v122
	v_lshlrev_b32_e32 v124, 16, v117
	v_fmac_f32_e32 v119, v123, v123
	v_and_b32_e32 v125, 0xffff0000, v117
	v_fmac_f32_e32 v119, v124, v124
	v_fmac_f32_e32 v119, v125, v125
	flat_store_dwordx4 v[128:129], v[114:117] offset:48
	v_add_f32_e32 v122, v137, v119
	ds_read_b128 v[114:117], v136 offset:128
	ds_read_b128 v[118:121], v136 offset:144
	v_lshlrev_b32_e32 v123, 16, v110
	v_and_b32_e32 v110, 0xffff0000, v110
	s_waitcnt lgkmcnt(0)
	v_add_f32_e32 v114, v114, v123
	v_add_f32_e32 v110, v115, v110
	v_cvt_pk_bf16_f32 v110, v114, v110
	v_lshlrev_b32_e32 v114, 16, v111
	v_and_b32_e32 v111, 0xffff0000, v111
	v_add_f32_e32 v114, v116, v114
	v_add_f32_e32 v111, v117, v111
	v_cvt_pk_bf16_f32 v111, v114, v111
	v_lshlrev_b32_e32 v114, 16, v112
	v_and_b32_e32 v112, 0xffff0000, v112
	v_add_f32_e32 v114, v118, v114
	v_add_f32_e32 v112, v119, v112
	v_cvt_pk_bf16_f32 v112, v114, v112
	v_lshlrev_b32_e32 v114, 16, v113
	v_and_b32_e32 v113, 0xffff0000, v113
	v_add_f32_e32 v114, v120, v114
	v_add_f32_e32 v113, v121, v113
	v_and_b32_e32 v115, 0xffff0000, v110
	v_cvt_pk_bf16_f32 v113, v114, v113
	v_lshlrev_b32_e32 v114, 16, v110
	v_mul_f32_e32 v115, v115, v115
	v_lshlrev_b32_e32 v116, 16, v111
	v_fmac_f32_e32 v115, v114, v114
	v_and_b32_e32 v117, 0xffff0000, v111
	v_fmac_f32_e32 v115, v116, v116
	v_lshlrev_b32_e32 v118, 16, v112
	v_fmac_f32_e32 v115, v117, v117
	v_and_b32_e32 v119, 0xffff0000, v112
	v_fmac_f32_e32 v115, v118, v118
	v_lshlrev_b32_e32 v120, 16, v113
	v_fmac_f32_e32 v115, v119, v119
	v_and_b32_e32 v121, 0xffff0000, v113
	v_fmac_f32_e32 v115, v120, v120
	v_fmac_f32_e32 v115, v121, v121
	flat_store_dwordx4 v[128:129], v[110:113] offset:64
	v_add_f32_e32 v118, v122, v115
	ds_read_b128 v[110:113], v136 offset:160
	ds_read_b128 v[114:117], v136 offset:176
	v_lshlrev_b32_e32 v119, 16, v106
	v_and_b32_e32 v106, 0xffff0000, v106
	s_waitcnt lgkmcnt(0)
	v_add_f32_e32 v110, v110, v119
	v_add_f32_e32 v106, v111, v106
	v_cvt_pk_bf16_f32 v106, v110, v106
	v_lshlrev_b32_e32 v110, 16, v107
	v_and_b32_e32 v107, 0xffff0000, v107
	v_add_f32_e32 v110, v112, v110
	v_add_f32_e32 v107, v113, v107
	v_cvt_pk_bf16_f32 v107, v110, v107
	v_lshlrev_b32_e32 v110, 16, v108
	v_and_b32_e32 v108, 0xffff0000, v108
	v_add_f32_e32 v110, v114, v110
	v_add_f32_e32 v108, v115, v108
	v_cvt_pk_bf16_f32 v108, v110, v108
	v_lshlrev_b32_e32 v110, 16, v109
	v_and_b32_e32 v109, 0xffff0000, v109
	v_add_f32_e32 v110, v116, v110
	v_add_f32_e32 v109, v117, v109
	v_and_b32_e32 v111, 0xffff0000, v106
	v_cvt_pk_bf16_f32 v109, v110, v109
	v_lshlrev_b32_e32 v110, 16, v106
	v_mul_f32_e32 v111, v111, v111
	v_lshlrev_b32_e32 v112, 16, v107
	v_fmac_f32_e32 v111, v110, v110
	v_and_b32_e32 v113, 0xffff0000, v107
	v_fmac_f32_e32 v111, v112, v112
	v_lshlrev_b32_e32 v114, 16, v108
	v_fmac_f32_e32 v111, v113, v113
	v_and_b32_e32 v115, 0xffff0000, v108
	v_fmac_f32_e32 v111, v114, v114
	v_lshlrev_b32_e32 v116, 16, v109
	v_fmac_f32_e32 v111, v115, v115
	v_and_b32_e32 v117, 0xffff0000, v109
	v_fmac_f32_e32 v111, v116, v116
	v_fmac_f32_e32 v111, v117, v117
	flat_store_dwordx4 v[128:129], v[106:109] offset:80
	v_add_f32_e32 v114, v118, v111
	ds_read_b128 v[106:109], v136 offset:192
	ds_read_b128 v[110:113], v136 offset:208
	v_lshlrev_b32_e32 v115, 16, v102
	v_and_b32_e32 v102, 0xffff0000, v102
	s_waitcnt lgkmcnt(0)
	v_add_f32_e32 v106, v106, v115
	v_add_f32_e32 v102, v107, v102
	v_cvt_pk_bf16_f32 v102, v106, v102
	v_lshlrev_b32_e32 v106, 16, v103
	v_and_b32_e32 v103, 0xffff0000, v103
	v_add_f32_e32 v106, v108, v106
	v_add_f32_e32 v103, v109, v103
	v_cvt_pk_bf16_f32 v103, v106, v103
	v_lshlrev_b32_e32 v106, 16, v104
	v_and_b32_e32 v104, 0xffff0000, v104
	v_add_f32_e32 v106, v110, v106
	v_add_f32_e32 v104, v111, v104
	v_cvt_pk_bf16_f32 v104, v106, v104
	v_lshlrev_b32_e32 v106, 16, v105
	v_and_b32_e32 v105, 0xffff0000, v105
	v_add_f32_e32 v106, v112, v106
	v_add_f32_e32 v105, v113, v105
	v_and_b32_e32 v107, 0xffff0000, v102
	v_cvt_pk_bf16_f32 v105, v106, v105
	v_lshlrev_b32_e32 v106, 16, v102
	v_mul_f32_e32 v107, v107, v107
	v_lshlrev_b32_e32 v108, 16, v103
	v_fmac_f32_e32 v107, v106, v106
	v_and_b32_e32 v109, 0xffff0000, v103
	v_fmac_f32_e32 v107, v108, v108
	v_lshlrev_b32_e32 v110, 16, v104
	v_fmac_f32_e32 v107, v109, v109
	v_and_b32_e32 v111, 0xffff0000, v104
	v_fmac_f32_e32 v107, v110, v110
	v_lshlrev_b32_e32 v112, 16, v105
	v_fmac_f32_e32 v107, v111, v111
	v_and_b32_e32 v113, 0xffff0000, v105
	v_fmac_f32_e32 v107, v112, v112
	v_fmac_f32_e32 v107, v113, v113
	flat_store_dwordx4 v[128:129], v[102:105] offset:96
	v_add_f32_e32 v110, v114, v107
	ds_read_b128 v[102:105], v136 offset:224
	ds_read_b128 v[106:109], v136 offset:240
	v_lshlrev_b32_e32 v111, 16, v98
	v_and_b32_e32 v98, 0xffff0000, v98
	s_waitcnt lgkmcnt(0)
	v_add_f32_e32 v102, v102, v111
	v_add_f32_e32 v98, v103, v98
	v_cvt_pk_bf16_f32 v98, v102, v98
	v_lshlrev_b32_e32 v102, 16, v99
	v_and_b32_e32 v99, 0xffff0000, v99
	v_add_f32_e32 v102, v104, v102
	v_add_f32_e32 v99, v105, v99
	v_cvt_pk_bf16_f32 v99, v102, v99
	v_lshlrev_b32_e32 v102, 16, v100
	v_and_b32_e32 v100, 0xffff0000, v100
	v_add_f32_e32 v102, v106, v102
	v_add_f32_e32 v100, v107, v100
	v_cvt_pk_bf16_f32 v100, v102, v100
	v_lshlrev_b32_e32 v102, 16, v101
	v_and_b32_e32 v101, 0xffff0000, v101
	v_add_f32_e32 v102, v108, v102
	v_add_f32_e32 v101, v109, v101
	v_and_b32_e32 v103, 0xffff0000, v98
	v_cvt_pk_bf16_f32 v101, v102, v101
	v_lshlrev_b32_e32 v102, 16, v98
	v_mul_f32_e32 v103, v103, v103
	v_lshlrev_b32_e32 v104, 16, v99
	v_fmac_f32_e32 v103, v102, v102
	v_and_b32_e32 v105, 0xffff0000, v99
	v_fmac_f32_e32 v103, v104, v104
	v_lshlrev_b32_e32 v106, 16, v100
	v_fmac_f32_e32 v103, v105, v105
	v_and_b32_e32 v107, 0xffff0000, v100
	v_fmac_f32_e32 v103, v106, v106
	v_lshlrev_b32_e32 v108, 16, v101
	v_fmac_f32_e32 v103, v107, v107
	v_and_b32_e32 v109, 0xffff0000, v101
	v_fmac_f32_e32 v103, v108, v108
	flat_store_dwordx4 v[128:129], v[98:101] offset:112
	v_fmac_f32_e32 v103, v109, v109
	v_add_f32_e32 v102, v110, v103
	v_lshlrev_b64 v[98:99], 6, v[126:127]
	v_lshl_add_u64 v[98:99], s[6:7], 0, v[98:99]
	v_lshl_add_u64 v[98:99], v[98:99], 0, s[16:17]
	flat_store_dword v[98:99], v102
	s_waitcnt lgkmcnt(0)
	s_barrier
	ds_write2_b32 v1, v62, v74 offset1:16
	ds_write2_b32 v1, v63, v75 offset0:68 offset1:84
	ds_write2_b32 v1, v64, v76 offset0:136 offset1:152
	ds_write2_b32 v1, v65, v77 offset0:204 offset1:220
	ds_write2_b32 v1, v78, v82 offset0:32 offset1:48
	ds_write2_b32 v1, v79, v83 offset0:100 offset1:116
	ds_write2_b32 v1, v80, v84 offset0:168 offset1:184
	ds_write2_b32 v1, v81, v85 offset0:236 offset1:252
	ds_write2_b32 v130, v46, v54 offset0:64 offset1:80
	ds_write2_b32 v130, v47, v55 offset0:132 offset1:148
	ds_write2_b32 v130, v48, v56 offset0:200 offset1:216
	ds_write2_b32 v131, v49, v57 offset0:12 offset1:28
	ds_write2_b32 v130, v58, v66 offset0:96 offset1:112
	ds_write2_b32 v130, v59, v67 offset0:164 offset1:180
	ds_write2_b32 v130, v60, v68 offset0:232 offset1:248
	ds_write2_b32 v131, v61, v69 offset0:44 offset1:60
	ds_write2_b32 v132, v30, v38 offset0:128 offset1:144
	ds_write2_b32 v132, v31, v39 offset0:196 offset1:212
	ds_write2_b32 v133, v32, v40 offset0:8 offset1:24
	ds_write2_b32 v133, v33, v41 offset0:76 offset1:92
	ds_write2_b32 v132, v42, v50 offset0:160 offset1:176
	ds_write2_b32 v132, v43, v51 offset0:228 offset1:244
	ds_write2_b32 v133, v44, v52 offset0:40 offset1:56
	ds_write2_b32 v133, v45, v53 offset0:108 offset1:124
	ds_write2_b32 v135, v18, v22 offset0:192 offset1:208
	ds_write2_b32 v134, v19, v23 offset0:4 offset1:20
	ds_write2_b32 v134, v20, v24 offset0:72 offset1:88
	ds_write2_b32 v134, v21, v25 offset0:140 offset1:156
	ds_write2_b32 v135, v26, v34 offset0:224 offset1:240
	ds_write2_b32 v134, v27, v35 offset0:36 offset1:52
	ds_write2_b32 v134, v28, v36 offset0:104 offset1:120
	ds_write2_b32 v134, v29, v37 offset0:172 offset1:188
	v_mov_b32_e32 v1, v170
	s_waitcnt lgkmcnt(0)
	s_barrier
	s_waitcnt vmcnt(0)
	v_lshlrev_b32_e32 v28, 16, v94
	v_add_u32_e32 v18, s4, v1
	v_ashrrev_i32_e32 v19, 31, v18
	v_lshlrev_b64 v[20:21], 11, v[18:19]
	v_lshl_add_u64 v[20:21], s[38:39], 0, v[20:21]
	v_mul_lo_u32 v1, v1, s33
	v_lshl_add_u64 v[32:33], v[20:21], 0, s[18:19]
	ds_read_b128 v[20:23], v1
	ds_read_b128 v[24:27], v1 offset:16
	s_mov_b64 s[4:5], 0
	s_waitcnt lgkmcnt(1)
	v_add_f32_e32 v20, v20, v28
	v_and_b32_e32 v28, 0xffff0000, v94
	v_add_f32_e32 v21, v21, v28
	v_cvt_pk_bf16_f32 v28, v20, v21
	v_and_b32_e32 v21, 0xffff0000, v95
	v_lshlrev_b32_e32 v20, 16, v95
	v_add_f32_e32 v21, v23, v21
	v_add_f32_e32 v20, v22, v20
	v_cvt_pk_bf16_f32 v29, v20, v21
	v_and_b32_e32 v21, 0xffff0000, v96
	v_lshlrev_b32_e32 v20, 16, v96
	s_waitcnt lgkmcnt(0)
	v_add_f32_e32 v21, v25, v21
	v_add_f32_e32 v20, v24, v20
	v_cvt_pk_bf16_f32 v30, v20, v21
	v_and_b32_e32 v21, 0xffff0000, v97
	v_lshlrev_b32_e32 v20, 16, v97
	v_add_f32_e32 v21, v27, v21
	v_add_f32_e32 v20, v26, v20
	v_cvt_pk_bf16_f32 v31, v20, v21
	v_and_b32_e32 v21, 0xffff0000, v28
	v_lshlrev_b32_e32 v20, 16, v28
	v_mul_f32_e32 v34, v21, v21
	v_lshlrev_b32_e32 v22, 16, v29
	v_fmac_f32_e32 v34, v20, v20
	v_and_b32_e32 v23, 0xffff0000, v29
	v_fmac_f32_e32 v34, v22, v22
	v_lshlrev_b32_e32 v24, 16, v30
	v_fmac_f32_e32 v34, v23, v23
	v_and_b32_e32 v25, 0xffff0000, v30
	v_fmac_f32_e32 v34, v24, v24
	v_add_co_u32_e32 v20, vcc, s90, v32
	v_lshlrev_b32_e32 v26, 16, v31
	v_fmac_f32_e32 v34, v25, v25
	v_addc_co_u32_e32 v21, vcc, 0, v33, vcc
	v_and_b32_e32 v27, 0xffff0000, v31
	v_fmac_f32_e32 v34, v26, v26
	flat_store_dwordx4 v[20:21], v[28:31] offset:128
	v_fmac_f32_e32 v34, v27, v27
	ds_read_b128 v[22:25], v1 offset:32
	ds_read_b128 v[26:29], v1 offset:48
	v_lshlrev_b32_e32 v30, 16, v90
	s_waitcnt lgkmcnt(0)
	v_add_f32_e32 v22, v22, v30
	v_and_b32_e32 v30, 0xffff0000, v90
	v_add_f32_e32 v23, v23, v30
	v_cvt_pk_bf16_f32 v22, v22, v23
	v_lshlrev_b32_e32 v23, 16, v91
	v_add_f32_e32 v23, v24, v23
	v_and_b32_e32 v24, 0xffff0000, v91
	v_add_f32_e32 v24, v25, v24
	v_cvt_pk_bf16_f32 v23, v23, v24
	v_lshlrev_b32_e32 v24, 16, v92
	v_and_b32_e32 v25, 0xffff0000, v92
	v_add_f32_e32 v24, v26, v24
	v_add_f32_e32 v25, v27, v25
	v_cvt_pk_bf16_f32 v24, v24, v25
	v_lshlrev_b32_e32 v25, 16, v93
	v_and_b32_e32 v26, 0xffff0000, v93
	v_add_f32_e32 v25, v28, v25
	v_add_f32_e32 v26, v29, v26
	v_and_b32_e32 v27, 0xffff0000, v22
	v_cvt_pk_bf16_f32 v25, v25, v26
	v_lshlrev_b32_e32 v26, 16, v22
	v_mul_f32_e32 v27, v27, v27
	v_lshlrev_b32_e32 v28, 16, v23
	v_fmac_f32_e32 v27, v26, v26
	v_and_b32_e32 v29, 0xffff0000, v23
	v_fmac_f32_e32 v27, v28, v28
	v_lshlrev_b32_e32 v30, 16, v24
	v_fmac_f32_e32 v27, v29, v29
	v_and_b32_e32 v31, 0xffff0000, v24
	v_fmac_f32_e32 v27, v30, v30
	v_lshlrev_b32_e32 v32, 16, v25
	v_fmac_f32_e32 v27, v31, v31
	v_and_b32_e32 v33, 0xffff0000, v25
	v_fmac_f32_e32 v27, v32, v32
	v_fmac_f32_e32 v27, v33, v33
	flat_store_dwordx4 v[20:21], v[22:25] offset:144
	v_add_f32_e32 v30, v34, v27
	ds_read_b128 v[22:25], v1 offset:64
	ds_read_b128 v[26:29], v1 offset:80
	v_lshlrev_b32_e32 v31, 16, v86
	s_waitcnt lgkmcnt(0)
	v_add_f32_e32 v22, v22, v31
	v_and_b32_e32 v31, 0xffff0000, v86
	v_add_f32_e32 v23, v23, v31
	v_cvt_pk_bf16_f32 v22, v22, v23
	v_lshlrev_b32_e32 v23, 16, v87
	v_add_f32_e32 v23, v24, v23
	v_and_b32_e32 v24, 0xffff0000, v87
	v_add_f32_e32 v24, v25, v24
	v_cvt_pk_bf16_f32 v23, v23, v24
	v_lshlrev_b32_e32 v24, 16, v88
	v_and_b32_e32 v25, 0xffff0000, v88
	v_add_f32_e32 v24, v26, v24
	v_add_f32_e32 v25, v27, v25
	v_cvt_pk_bf16_f32 v24, v24, v25
	v_lshlrev_b32_e32 v25, 16, v89
	v_and_b32_e32 v26, 0xffff0000, v89
	v_add_f32_e32 v25, v28, v25
	v_add_f32_e32 v26, v29, v26
	v_and_b32_e32 v27, 0xffff0000, v22
	v_cvt_pk_bf16_f32 v25, v25, v26
	v_lshlrev_b32_e32 v26, 16, v22
	v_mul_f32_e32 v27, v27, v27
	v_lshlrev_b32_e32 v28, 16, v23
	v_fmac_f32_e32 v27, v26, v26
	v_and_b32_e32 v29, 0xffff0000, v23
	v_fmac_f32_e32 v27, v28, v28
	v_lshlrev_b32_e32 v31, 16, v24
	v_fmac_f32_e32 v27, v29, v29
	v_and_b32_e32 v32, 0xffff0000, v24
	v_fmac_f32_e32 v27, v31, v31
	v_lshlrev_b32_e32 v33, 16, v25
	v_fmac_f32_e32 v27, v32, v32
	v_and_b32_e32 v34, 0xffff0000, v25
	v_fmac_f32_e32 v27, v33, v33
	v_fmac_f32_e32 v27, v34, v34
	flat_store_dwordx4 v[20:21], v[22:25] offset:160
	v_add_f32_e32 v30, v30, v27
	ds_read_b128 v[22:25], v1 offset:96
	ds_read_b128 v[26:29], v1 offset:112
	v_lshlrev_b32_e32 v31, 16, v70
	s_waitcnt lgkmcnt(0)
	v_add_f32_e32 v22, v22, v31
	v_and_b32_e32 v31, 0xffff0000, v70
	v_add_f32_e32 v23, v23, v31
	v_cvt_pk_bf16_f32 v22, v22, v23
	v_lshlrev_b32_e32 v23, 16, v71
	v_add_f32_e32 v23, v24, v23
	v_and_b32_e32 v24, 0xffff0000, v71
	v_add_f32_e32 v24, v25, v24
	v_cvt_pk_bf16_f32 v23, v23, v24
	v_lshlrev_b32_e32 v24, 16, v72
	v_and_b32_e32 v25, 0xffff0000, v72
	v_add_f32_e32 v24, v26, v24
	v_add_f32_e32 v25, v27, v25
	v_cvt_pk_bf16_f32 v24, v24, v25
	v_lshlrev_b32_e32 v25, 16, v73
	v_and_b32_e32 v26, 0xffff0000, v73
	v_add_f32_e32 v25, v28, v25
	v_add_f32_e32 v26, v29, v26
	v_and_b32_e32 v27, 0xffff0000, v22
	v_cvt_pk_bf16_f32 v25, v25, v26
	v_lshlrev_b32_e32 v26, 16, v22
	v_mul_f32_e32 v27, v27, v27
	v_lshlrev_b32_e32 v28, 16, v23
	v_fmac_f32_e32 v27, v26, v26
	v_and_b32_e32 v29, 0xffff0000, v23
	v_fmac_f32_e32 v27, v28, v28
	v_lshlrev_b32_e32 v31, 16, v24
	v_fmac_f32_e32 v27, v29, v29
	v_and_b32_e32 v32, 0xffff0000, v24
	v_fmac_f32_e32 v27, v31, v31
	v_lshlrev_b32_e32 v33, 16, v25
	v_fmac_f32_e32 v27, v32, v32
	v_and_b32_e32 v34, 0xffff0000, v25
	v_fmac_f32_e32 v27, v33, v33
	v_fmac_f32_e32 v27, v34, v34
	flat_store_dwordx4 v[20:21], v[22:25] offset:176
	v_add_f32_e32 v30, v30, v27
	ds_read_b128 v[22:25], v1 offset:128
	ds_read_b128 v[26:29], v1 offset:144
	v_lshlrev_b32_e32 v31, 16, v14
	v_and_b32_e32 v14, 0xffff0000, v14
	s_waitcnt lgkmcnt(0)
	v_add_f32_e32 v22, v22, v31
	v_add_f32_e32 v14, v23, v14
	v_cvt_pk_bf16_f32 v14, v22, v14
	v_lshlrev_b32_e32 v22, 16, v15
	v_and_b32_e32 v15, 0xffff0000, v15
	v_add_f32_e32 v22, v24, v22
	v_add_f32_e32 v15, v25, v15
	v_cvt_pk_bf16_f32 v15, v22, v15
	v_lshlrev_b32_e32 v22, 16, v16
	v_and_b32_e32 v16, 0xffff0000, v16
	v_add_f32_e32 v22, v26, v22
	v_add_f32_e32 v16, v27, v16
	v_cvt_pk_bf16_f32 v16, v22, v16
	v_lshlrev_b32_e32 v22, 16, v17
	v_and_b32_e32 v17, 0xffff0000, v17
	v_add_f32_e32 v22, v28, v22
	v_add_f32_e32 v17, v29, v17
	v_and_b32_e32 v23, 0xffff0000, v14
	v_cvt_pk_bf16_f32 v17, v22, v17
	v_lshlrev_b32_e32 v22, 16, v14
	v_mul_f32_e32 v23, v23, v23
	v_lshlrev_b32_e32 v24, 16, v15
	v_fmac_f32_e32 v23, v22, v22
	v_and_b32_e32 v25, 0xffff0000, v15
	v_fmac_f32_e32 v23, v24, v24
	v_lshlrev_b32_e32 v26, 16, v16
	v_fmac_f32_e32 v23, v25, v25
	v_and_b32_e32 v27, 0xffff0000, v16
	v_fmac_f32_e32 v23, v26, v26
	v_lshlrev_b32_e32 v28, 16, v17
	v_fmac_f32_e32 v23, v27, v27
	v_and_b32_e32 v29, 0xffff0000, v17
	v_fmac_f32_e32 v23, v28, v28
	v_fmac_f32_e32 v23, v29, v29
	flat_store_dwordx4 v[20:21], v[14:17] offset:192
	v_add_f32_e32 v26, v30, v23
	ds_read_b128 v[14:17], v1 offset:160
	ds_read_b128 v[22:25], v1 offset:176
	v_lshlrev_b32_e32 v27, 16, v10
	v_and_b32_e32 v10, 0xffff0000, v10
	s_waitcnt lgkmcnt(0)
	v_add_f32_e32 v14, v14, v27
	v_add_f32_e32 v10, v15, v10
	v_cvt_pk_bf16_f32 v10, v14, v10
	v_lshlrev_b32_e32 v14, 16, v11
	v_and_b32_e32 v11, 0xffff0000, v11
	v_add_f32_e32 v14, v16, v14
	v_add_f32_e32 v11, v17, v11
	v_cvt_pk_bf16_f32 v11, v14, v11
	v_lshlrev_b32_e32 v14, 16, v12
	v_and_b32_e32 v12, 0xffff0000, v12
	v_add_f32_e32 v14, v22, v14
	v_add_f32_e32 v12, v23, v12
	v_cvt_pk_bf16_f32 v12, v14, v12
	v_lshlrev_b32_e32 v14, 16, v13
	v_and_b32_e32 v13, 0xffff0000, v13
	v_add_f32_e32 v14, v24, v14
	v_add_f32_e32 v13, v25, v13
	v_and_b32_e32 v15, 0xffff0000, v10
	v_cvt_pk_bf16_f32 v13, v14, v13
	v_lshlrev_b32_e32 v14, 16, v10
	v_mul_f32_e32 v15, v15, v15
	v_lshlrev_b32_e32 v16, 16, v11
	v_fmac_f32_e32 v15, v14, v14
	v_and_b32_e32 v17, 0xffff0000, v11
	v_fmac_f32_e32 v15, v16, v16
	v_lshlrev_b32_e32 v22, 16, v12
	v_fmac_f32_e32 v15, v17, v17
	v_and_b32_e32 v23, 0xffff0000, v12
	v_fmac_f32_e32 v15, v22, v22
	v_lshlrev_b32_e32 v24, 16, v13
	v_fmac_f32_e32 v15, v23, v23
	v_and_b32_e32 v25, 0xffff0000, v13
	v_fmac_f32_e32 v15, v24, v24
	v_fmac_f32_e32 v15, v25, v25
	flat_store_dwordx4 v[20:21], v[10:13] offset:208
	v_add_f32_e32 v22, v26, v15
	ds_read_b128 v[10:13], v1 offset:192
	ds_read_b128 v[14:17], v1 offset:208
	v_lshlrev_b32_e32 v23, 16, v6
	v_and_b32_e32 v6, 0xffff0000, v6
	s_waitcnt lgkmcnt(0)
	v_add_f32_e32 v10, v10, v23
	v_add_f32_e32 v6, v11, v6
	v_cvt_pk_bf16_f32 v6, v10, v6
	v_lshlrev_b32_e32 v10, 16, v7
	v_and_b32_e32 v7, 0xffff0000, v7
	v_add_f32_e32 v10, v12, v10
	v_add_f32_e32 v7, v13, v7
	v_cvt_pk_bf16_f32 v7, v10, v7
	v_lshlrev_b32_e32 v10, 16, v8
	v_and_b32_e32 v8, 0xffff0000, v8
	v_add_f32_e32 v10, v14, v10
	v_add_f32_e32 v8, v15, v8
	v_cvt_pk_bf16_f32 v8, v10, v8
	v_lshlrev_b32_e32 v10, 16, v9
	v_and_b32_e32 v9, 0xffff0000, v9
	v_add_f32_e32 v10, v16, v10
	v_add_f32_e32 v9, v17, v9
	v_and_b32_e32 v11, 0xffff0000, v6
	v_cvt_pk_bf16_f32 v9, v10, v9
	v_lshlrev_b32_e32 v10, 16, v6
	v_mul_f32_e32 v11, v11, v11
	v_lshlrev_b32_e32 v12, 16, v7
	v_fmac_f32_e32 v11, v10, v10
	v_and_b32_e32 v13, 0xffff0000, v7
	v_fmac_f32_e32 v11, v12, v12
	v_lshlrev_b32_e32 v14, 16, v8
	v_fmac_f32_e32 v11, v13, v13
	v_and_b32_e32 v15, 0xffff0000, v8
	v_fmac_f32_e32 v11, v14, v14
	v_lshlrev_b32_e32 v16, 16, v9
	v_fmac_f32_e32 v11, v15, v15
	v_and_b32_e32 v17, 0xffff0000, v9
	v_fmac_f32_e32 v11, v16, v16
	v_fmac_f32_e32 v11, v17, v17
	flat_store_dwordx4 v[20:21], v[6:9] offset:224
	v_add_f32_e32 v14, v22, v11
	ds_read_b128 v[6:9], v1 offset:224
	ds_read_b128 v[10:13], v1 offset:240
	v_lshlrev_b32_e32 v1, 16, v2
	v_and_b32_e32 v2, 0xffff0000, v2
	s_waitcnt lgkmcnt(0)
	v_add_f32_e32 v1, v6, v1
	v_add_f32_e32 v2, v7, v2
	v_cvt_pk_bf16_f32 v2, v1, v2
	v_lshlrev_b32_e32 v1, 16, v3
	v_and_b32_e32 v3, 0xffff0000, v3
	v_add_f32_e32 v1, v8, v1
	v_add_f32_e32 v3, v9, v3
	v_cvt_pk_bf16_f32 v3, v1, v3
	v_lshlrev_b32_e32 v1, 16, v4
	v_and_b32_e32 v4, 0xffff0000, v4
	v_add_f32_e32 v1, v10, v1
	v_add_f32_e32 v4, v11, v4
	v_cvt_pk_bf16_f32 v4, v1, v4
	v_lshlrev_b32_e32 v1, 16, v5
	v_and_b32_e32 v5, 0xffff0000, v5
	v_add_f32_e32 v1, v12, v1
	v_add_f32_e32 v5, v13, v5
	v_and_b32_e32 v6, 0xffff0000, v2
	v_cvt_pk_bf16_f32 v5, v1, v5
	v_lshlrev_b32_e32 v1, 16, v2
	v_mul_f32_e32 v6, v6, v6
	v_lshlrev_b32_e32 v7, 16, v3
	v_fmac_f32_e32 v6, v1, v1
	v_and_b32_e32 v8, 0xffff0000, v3
	v_fmac_f32_e32 v6, v7, v7
	v_lshlrev_b32_e32 v9, 16, v4
	v_fmac_f32_e32 v6, v8, v8
	v_and_b32_e32 v10, 0xffff0000, v4
	v_fmac_f32_e32 v6, v9, v9
	v_lshlrev_b32_e32 v11, 16, v5
	v_fmac_f32_e32 v6, v10, v10
	v_and_b32_e32 v12, 0xffff0000, v5
	v_fmac_f32_e32 v6, v11, v11
	flat_store_dwordx4 v[20:21], v[2:5] offset:240
	v_fmac_f32_e32 v6, v12, v12
	v_add_f32_e32 v1, v14, v6
	v_lshlrev_b64 v[2:3], 6, v[18:19]
	v_lshl_add_u64 v[2:3], s[6:7], 0, v[2:3]
	v_lshl_add_u64 v[2:3], v[2:3], 0, s[16:17]
	flat_store_dword v[2:3], v1 offset:4
	s_branch .LBB0_457
